# v58 + phases 2/4 of the GEMM K-loop: DMA address VALU moved from the segment head to after the 8 ds_reads
# baseline (speedup 1.0000x reference)
.LBB0_64:
	s_add_i32 s33, s42, 2
	s_add_u32 s46, s40, 0x80
	s_addc_u32 s43, s41, 0
	s_add_i32 s80, 0, 0x10000
	s_cmp_eq_u32 s84, s42
	s_cselect_b32 s43, s1, s43
	s_cselect_b32 s42, s0, s46
	s_cselect_b32 s47, s75, vcc_hi
	s_cselect_b32 s46, s74, vcc_lo
	s_add_i32 s5, 0, 0x14000
	ds_read_b128 v[128:131], v249
	ds_read_b128 v[132:135], v249 offset:1024
	ds_read_b128 v[136:139], v249 offset:2048
	ds_read_b128 v[140:143], v249 offset:3072
	ds_read_b128 v[144:147], v249 offset:16384
	ds_read_b128 v[148:151], v249 offset:17408
	ds_read_b128 v[152:155], v249 offset:18432
	ds_read_b128 v[166:169], v249 offset:19456
	v_lshl_add_u64 v[182:183], s[40:41], 0, v[162:163]
	s_add_i32 m0, s28, 0xc000
	ds_read_b128 v[170:173], v188
	ds_read_b128 v[174:177], v188 offset:1024
	ds_read_b128 v[178:181], v188 offset:2048
	ds_read_b128 v[214:217], v188 offset:3072
	ds_read_b128 v[218:221], v188 offset:4096
	ds_read_b128 v[222:225], v188 offset:5120
	ds_read_b128 v[226:229], v188 offset:6144
	ds_read_b128 v[230:233], v188 offset:7168
	global_load_lds_dwordx4 v[182:183], off
	v_lshl_add_u64 v[182:183], s[40:41], 0, v[164:165]
	s_add_i32 m0, s28, 0xe000
	s_nop 0
	global_load_lds_dwordx4 v[182:183], off
	s_waitcnt vmcnt(8)
	s_waitcnt lgkmcnt(0)
	s_barrier
	s_waitcnt lgkmcnt(0)
	v_mfma_f32_16x16x32_bf16 v[124:127], v[128:131], v[170:173], v[124:127]
	v_mfma_f32_16x16x32_bf16 v[120:123], v[136:139], v[170:173], v[120:123]
	v_mfma_f32_16x16x32_bf16 v[108:111], v[128:131], v[178:181], v[108:111]
	v_mfma_f32_16x16x32_bf16 v[104:107], v[136:139], v[178:181], v[104:107]
	v_mfma_f32_16x16x32_bf16 v[92:95], v[128:131], v[218:221], v[92:95]
	v_mfma_f32_16x16x32_bf16 v[88:91], v[136:139], v[218:221], v[88:91]
	v_mfma_f32_16x16x32_bf16 v[76:79], v[128:131], v[226:229], v[76:79]
	v_mfma_f32_16x16x32_bf16 v[72:75], v[136:139], v[226:229], v[72:75]
	v_mfma_f32_16x16x32_bf16 v[124:127], v[132:135], v[174:177], v[124:127]
	v_mfma_f32_16x16x32_bf16 v[120:123], v[140:143], v[174:177], v[120:123]
	v_mfma_f32_16x16x32_bf16 v[108:111], v[132:135], v[214:217], v[108:111]
	v_mfma_f32_16x16x32_bf16 v[104:107], v[140:143], v[214:217], v[104:107]
	v_mfma_f32_16x16x32_bf16 v[92:95], v[132:135], v[222:225], v[92:95]
	v_mfma_f32_16x16x32_bf16 v[88:91], v[140:143], v[222:225], v[88:91]
	v_mfma_f32_16x16x32_bf16 v[76:79], v[132:135], v[230:233], v[76:79]
	v_mfma_f32_16x16x32_bf16 v[72:75], v[140:143], v[230:233], v[72:75]
	v_mfma_f32_16x16x32_bf16 v[116:119], v[144:147], v[170:173], v[116:119]
	v_mfma_f32_16x16x32_bf16 v[112:115], v[152:155], v[170:173], v[112:115]
	v_mfma_f32_16x16x32_bf16 v[100:103], v[144:147], v[178:181], v[100:103]
	v_mfma_f32_16x16x32_bf16 v[96:99], v[152:155], v[178:181], v[96:99]
	v_mfma_f32_16x16x32_bf16 v[84:87], v[144:147], v[218:221], v[84:87]
	v_mfma_f32_16x16x32_bf16 v[80:83], v[152:155], v[218:221], v[80:83]
	v_mfma_f32_16x16x32_bf16 v[68:71], v[144:147], v[226:229], v[68:71]
	v_mfma_f32_16x16x32_bf16 v[64:67], v[152:155], v[226:229], v[64:67]
	v_mfma_f32_16x16x32_bf16 v[116:119], v[148:151], v[174:177], v[116:119]
	v_mfma_f32_16x16x32_bf16 v[112:115], v[166:169], v[174:177], v[112:115]
	v_mfma_f32_16x16x32_bf16 v[100:103], v[148:151], v[214:217], v[100:103]
	v_mfma_f32_16x16x32_bf16 v[96:99], v[166:169], v[214:217], v[96:99]
	v_mfma_f32_16x16x32_bf16 v[84:87], v[148:151], v[222:225], v[84:87]
	v_mfma_f32_16x16x32_bf16 v[80:83], v[166:169], v[222:225], v[80:83]
	v_mfma_f32_16x16x32_bf16 v[68:71], v[148:151], v[230:233], v[68:71]
	v_mfma_f32_16x16x32_bf16 v[64:67], v[166:169], v[230:233], v[64:67]
	s_barrier
	s_add_i32 s80, s80, s27
	s_mov_b32 m0, s80
	ds_read_b128 v[170:173], v188 offset:16384
	ds_read_b128 v[174:177], v188 offset:17408
	ds_read_b128 v[178:181], v188 offset:18432
	ds_read_b128 v[214:217], v188 offset:19456
	ds_read_b128 v[218:221], v188 offset:20480
	ds_read_b128 v[222:225], v188 offset:21504
	ds_read_b128 v[226:229], v188 offset:22528
	ds_read_b128 v[230:233], v188 offset:23552
	v_lshl_add_u64 v[182:183], s[46:47], 0, v[192:193]
	global_load_lds_dwordx4 v[182:183], off
	s_add_i32 m0, s80, 0x2000
	v_lshl_add_u64 v[190:191], s[46:47], 0, v[160:161]
	s_add_u32 s46, s46, s30
	s_addc_u32 s47, s47, 0
	s_add_i32 s5, s5, s27
	global_load_lds_dwordx4 v[190:191], off
	v_lshl_add_u64 v[200:201], s[46:47], 0, v[192:193]
	s_mov_b32 m0, s5
	v_lshl_add_u64 v[234:235], s[46:47], 0, v[160:161]
	global_load_lds_dwordx4 v[200:201], off
	s_add_i32 m0, s5, 0x2000
	v_lshl_add_u64 v[236:237], s[42:43], 0, v[156:157]
	global_load_lds_dwordx4 v[234:235], off
	s_mov_b32 m0, s28
	v_lshl_add_u64 v[238:239], s[42:43], 0, v[158:159]
	global_load_lds_dwordx4 v[236:237], off
	s_mov_b32 m0, s69
	s_nop 0
	global_load_lds_dwordx4 v[238:239], off
	s_waitcnt vmcnt(8)
	s_waitcnt lgkmcnt(0)
	s_barrier
	s_waitcnt lgkmcnt(0)
	v_mfma_f32_16x16x32_bf16 v[60:63], v[128:131], v[170:173], v[60:63]
	v_mfma_f32_16x16x32_bf16 v[56:59], v[136:139], v[170:173], v[56:59]
	v_mfma_f32_16x16x32_bf16 v[44:47], v[128:131], v[178:181], v[44:47]
	v_mfma_f32_16x16x32_bf16 v[40:43], v[136:139], v[178:181], v[40:43]
	v_mfma_f32_16x16x32_bf16 v[28:31], v[128:131], v[218:221], v[28:31]
	v_mfma_f32_16x16x32_bf16 v[24:27], v[136:139], v[218:221], v[24:27]
	v_mfma_f32_16x16x32_bf16 v[12:15], v[128:131], v[226:229], v[12:15]
	v_mfma_f32_16x16x32_bf16 v[8:11], v[136:139], v[226:229], v[8:11]
	v_mfma_f32_16x16x32_bf16 v[60:63], v[132:135], v[174:177], v[60:63]
	v_mfma_f32_16x16x32_bf16 v[56:59], v[140:143], v[174:177], v[56:59]
	v_mfma_f32_16x16x32_bf16 v[44:47], v[132:135], v[214:217], v[44:47]
	v_mfma_f32_16x16x32_bf16 v[40:43], v[140:143], v[214:217], v[40:43]
	v_mfma_f32_16x16x32_bf16 v[28:31], v[132:135], v[222:225], v[28:31]
	v_mfma_f32_16x16x32_bf16 v[24:27], v[140:143], v[222:225], v[24:27]
	v_mfma_f32_16x16x32_bf16 v[12:15], v[132:135], v[230:233], v[12:15]
	v_mfma_f32_16x16x32_bf16 v[8:11], v[140:143], v[230:233], v[8:11]
	v_mfma_f32_16x16x32_bf16 v[52:55], v[144:147], v[170:173], v[52:55]
	v_mfma_f32_16x16x32_bf16 v[48:51], v[152:155], v[170:173], v[48:51]
	v_mfma_f32_16x16x32_bf16 v[36:39], v[144:147], v[178:181], v[36:39]
	v_mfma_f32_16x16x32_bf16 v[32:35], v[152:155], v[178:181], v[32:35]
	v_mfma_f32_16x16x32_bf16 v[20:23], v[144:147], v[218:221], v[20:23]
	v_mfma_f32_16x16x32_bf16 v[16:19], v[152:155], v[218:221], v[16:19]
	v_mfma_f32_16x16x32_bf16 v[4:7], v[144:147], v[226:229], v[4:7]
	v_mfma_f32_16x16x32_bf16 v[0:3], v[152:155], v[226:229], v[0:3]
	v_mfma_f32_16x16x32_bf16 v[52:55], v[148:151], v[174:177], v[52:55]
	v_mfma_f32_16x16x32_bf16 v[48:51], v[166:169], v[174:177], v[48:51]
	v_mfma_f32_16x16x32_bf16 v[36:39], v[148:151], v[214:217], v[36:39]
	v_mfma_f32_16x16x32_bf16 v[32:35], v[166:169], v[214:217], v[32:35]
	v_mfma_f32_16x16x32_bf16 v[20:23], v[148:151], v[222:225], v[20:23]
	v_mfma_f32_16x16x32_bf16 v[16:19], v[166:169], v[222:225], v[16:19]
	v_mfma_f32_16x16x32_bf16 v[4:7], v[148:151], v[230:233], v[4:7]
	v_mfma_f32_16x16x32_bf16 v[0:3], v[166:169], v[230:233], v[0:3]
	s_barrier
.Lmy_sp3:
	s_add_i32 s5, 0, 0x18000
	s_add_i32 s46, 0, 0x1c000
	ds_read_b128 v[128:131], v249 offset:32768
	ds_read_b128 v[132:135], v249 offset:33792
	ds_read_b128 v[136:139], v249 offset:34816
	ds_read_b128 v[140:143], v249 offset:35840
	ds_read_b128 v[144:147], v249 offset:49152
	ds_read_b128 v[148:151], v249 offset:50176
	ds_read_b128 v[152:155], v249 offset:51200
	ds_read_b128 v[166:169], v249 offset:52224
	s_add_u32 s42, s42, s30
	s_addc_u32 s43, s43, 0
	s_mov_b32 m0, s72
	v_lshl_add_u64 v[240:241], s[42:43], 0, v[156:157]
	ds_read_b128 v[170:173], v188 offset:32768
	ds_read_b128 v[174:177], v188 offset:33792
	ds_read_b128 v[178:181], v188 offset:34816
	ds_read_b128 v[214:217], v188 offset:35840
	ds_read_b128 v[218:221], v188 offset:36864
	ds_read_b128 v[222:225], v188 offset:37888
	ds_read_b128 v[226:229], v188 offset:38912
	ds_read_b128 v[230:233], v188 offset:39936
	global_load_lds_dwordx4 v[240:241], off
	v_lshl_add_u64 v[240:241], s[42:43], 0, v[158:159]
	s_mov_b32 m0, s76
	s_nop 0
	global_load_lds_dwordx4 v[240:241], off
	s_waitcnt vmcnt(8)
	s_waitcnt lgkmcnt(0)
	s_barrier
	s_waitcnt lgkmcnt(0)
	v_mfma_f32_16x16x32_bf16 v[124:127], v[128:131], v[170:173], v[124:127]
	v_mfma_f32_16x16x32_bf16 v[120:123], v[136:139], v[170:173], v[120:123]
	v_mfma_f32_16x16x32_bf16 v[108:111], v[128:131], v[178:181], v[108:111]
	v_mfma_f32_16x16x32_bf16 v[104:107], v[136:139], v[178:181], v[104:107]
	v_mfma_f32_16x16x32_bf16 v[92:95], v[128:131], v[218:221], v[92:95]
	v_mfma_f32_16x16x32_bf16 v[88:91], v[136:139], v[218:221], v[88:91]
	v_mfma_f32_16x16x32_bf16 v[76:79], v[128:131], v[226:229], v[76:79]
	v_mfma_f32_16x16x32_bf16 v[72:75], v[136:139], v[226:229], v[72:75]
	v_mfma_f32_16x16x32_bf16 v[124:127], v[132:135], v[174:177], v[124:127]
	v_mfma_f32_16x16x32_bf16 v[120:123], v[140:143], v[174:177], v[120:123]
	v_mfma_f32_16x16x32_bf16 v[108:111], v[132:135], v[214:217], v[108:111]
	v_mfma_f32_16x16x32_bf16 v[104:107], v[140:143], v[214:217], v[104:107]
	v_mfma_f32_16x16x32_bf16 v[92:95], v[132:135], v[222:225], v[92:95]
	v_mfma_f32_16x16x32_bf16 v[88:91], v[140:143], v[222:225], v[88:91]
	v_mfma_f32_16x16x32_bf16 v[76:79], v[132:135], v[230:233], v[76:79]
	v_mfma_f32_16x16x32_bf16 v[72:75], v[140:143], v[230:233], v[72:75]
	v_mfma_f32_16x16x32_bf16 v[116:119], v[144:147], v[170:173], v[116:119]
	v_mfma_f32_16x16x32_bf16 v[112:115], v[152:155], v[170:173], v[112:115]
	v_mfma_f32_16x16x32_bf16 v[100:103], v[144:147], v[178:181], v[100:103]
	v_mfma_f32_16x16x32_bf16 v[96:99], v[152:155], v[178:181], v[96:99]
	v_mfma_f32_16x16x32_bf16 v[84:87], v[144:147], v[218:221], v[84:87]
	v_mfma_f32_16x16x32_bf16 v[80:83], v[152:155], v[218:221], v[80:83]
	v_mfma_f32_16x16x32_bf16 v[68:71], v[144:147], v[226:229], v[68:71]
	v_mfma_f32_16x16x32_bf16 v[64:67], v[152:155], v[226:229], v[64:67]
	v_mfma_f32_16x16x32_bf16 v[116:119], v[148:151], v[174:177], v[116:119]
	v_mfma_f32_16x16x32_bf16 v[112:115], v[166:169], v[174:177], v[112:115]
	v_mfma_f32_16x16x32_bf16 v[100:103], v[148:151], v[214:217], v[100:103]
	v_mfma_f32_16x16x32_bf16 v[96:99], v[166:169], v[214:217], v[96:99]
	v_mfma_f32_16x16x32_bf16 v[84:87], v[148:151], v[222:225], v[84:87]
	v_mfma_f32_16x16x32_bf16 v[80:83], v[166:169], v[222:225], v[80:83]
	v_mfma_f32_16x16x32_bf16 v[68:71], v[148:151], v[230:233], v[68:71]
	v_mfma_f32_16x16x32_bf16 v[64:67], v[166:169], v[230:233], v[64:67]
	s_barrier
	s_add_i32 s5, s5, s27
	s_mov_b32 m0, s5
	ds_read_b128 v[170:173], v188 offset:49152
	ds_read_b128 v[174:177], v188 offset:50176
	ds_read_b128 v[178:181], v188 offset:51200
	ds_read_b128 v[214:217], v188 offset:52224
	ds_read_b128 v[218:221], v188 offset:53248
	ds_read_b128 v[222:225], v188 offset:54272
	ds_read_b128 v[226:229], v188 offset:55296
	ds_read_b128 v[230:233], v188 offset:56320
	v_lshl_add_u64 v[182:183], v[182:183], 0, s[70:71]
	global_load_lds_dwordx4 v[182:183], off
	v_lshl_add_u64 v[182:183], v[190:191], 0, s[70:71]
	s_add_i32 m0, s5, 0x2000
	s_add_i32 s5, s46, s27
	global_load_lds_dwordx4 v[182:183], off
	v_lshl_add_u64 v[182:183], v[200:201], 0, s[70:71]
	s_mov_b32 m0, s5
	s_nop 0
	global_load_lds_dwordx4 v[182:183], off
	v_lshl_add_u64 v[182:183], v[234:235], 0, s[70:71]
	s_add_i32 m0, s5, 0x2000
	s_nop 0
	global_load_lds_dwordx4 v[182:183], off
	v_lshl_add_u64 v[182:183], v[236:237], 0, s[70:71]
	s_mov_b32 m0, s81
	s_nop 0
	global_load_lds_dwordx4 v[182:183], off
	v_lshl_add_u64 v[182:183], v[238:239], 0, s[70:71]
	s_mov_b32 m0, s82
	s_nop 0
	global_load_lds_dwordx4 v[182:183], off
	s_waitcnt vmcnt(8)
	s_waitcnt lgkmcnt(0)
	s_barrier
	s_waitcnt lgkmcnt(0)
	v_mfma_f32_16x16x32_bf16 v[60:63], v[128:131], v[170:173], v[60:63]
	v_mfma_f32_16x16x32_bf16 v[56:59], v[136:139], v[170:173], v[56:59]
	v_mfma_f32_16x16x32_bf16 v[44:47], v[128:131], v[178:181], v[44:47]
	v_mfma_f32_16x16x32_bf16 v[40:43], v[136:139], v[178:181], v[40:43]
	v_mfma_f32_16x16x32_bf16 v[28:31], v[128:131], v[218:221], v[28:31]
	v_mfma_f32_16x16x32_bf16 v[24:27], v[136:139], v[218:221], v[24:27]
	v_mfma_f32_16x16x32_bf16 v[12:15], v[128:131], v[226:229], v[12:15]
	v_mfma_f32_16x16x32_bf16 v[8:11], v[136:139], v[226:229], v[8:11]
	v_mfma_f32_16x16x32_bf16 v[60:63], v[132:135], v[174:177], v[60:63]
	v_mfma_f32_16x16x32_bf16 v[56:59], v[140:143], v[174:177], v[56:59]
	v_mfma_f32_16x16x32_bf16 v[44:47], v[132:135], v[214:217], v[44:47]
	v_mfma_f32_16x16x32_bf16 v[40:43], v[140:143], v[214:217], v[40:43]
	v_mfma_f32_16x16x32_bf16 v[28:31], v[132:135], v[222:225], v[28:31]
	v_mfma_f32_16x16x32_bf16 v[24:27], v[140:143], v[222:225], v[24:27]
	v_mfma_f32_16x16x32_bf16 v[12:15], v[132:135], v[230:233], v[12:15]
	v_mfma_f32_16x16x32_bf16 v[8:11], v[140:143], v[230:233], v[8:11]
	v_mfma_f32_16x16x32_bf16 v[52:55], v[144:147], v[170:173], v[52:55]
	v_mfma_f32_16x16x32_bf16 v[48:51], v[152:155], v[170:173], v[48:51]
	v_mfma_f32_16x16x32_bf16 v[36:39], v[144:147], v[178:181], v[36:39]
	v_mfma_f32_16x16x32_bf16 v[32:35], v[152:155], v[178:181], v[32:35]
	v_mfma_f32_16x16x32_bf16 v[20:23], v[144:147], v[218:221], v[20:23]
	v_mfma_f32_16x16x32_bf16 v[16:19], v[152:155], v[218:221], v[16:19]
	v_mfma_f32_16x16x32_bf16 v[4:7], v[144:147], v[226:229], v[4:7]
	v_mfma_f32_16x16x32_bf16 v[0:3], v[152:155], v[226:229], v[0:3]
	v_mfma_f32_16x16x32_bf16 v[52:55], v[148:151], v[174:177], v[52:55]
	v_mfma_f32_16x16x32_bf16 v[48:51], v[166:169], v[174:177], v[48:51]
	v_mfma_f32_16x16x32_bf16 v[36:39], v[148:151], v[214:217], v[36:39]
	v_mfma_f32_16x16x32_bf16 v[32:35], v[166:169], v[214:217], v[32:35]
	v_mfma_f32_16x16x32_bf16 v[20:23], v[148:151], v[222:225], v[20:23]
	v_mfma_f32_16x16x32_bf16 v[16:19], v[166:169], v[222:225], v[16:19]
	v_mfma_f32_16x16x32_bf16 v[4:7], v[148:151], v[230:233], v[4:7]
	v_mfma_f32_16x16x32_bf16 v[0:3], v[166:169], v[230:233], v[0:3]
	s_barrier
	s_add_u32 s40, s40, 0x100
	s_addc_u32 s41, s41, 0
	s_add_u32 vcc_lo, vcc_lo, 0x100
	s_addc_u32 vcc_hi, vcc_hi, 0
	s_cmp_ge_u32 s33, s78
	s_mov_b32 s42, s33
	s_cbranch_scc0 .LBB0_64
	s_and_b64 vcc, exec, s[66:67]
	s_cbranch_vccz .LBB0_67
	s_barrier

.Lmy_peel:
	s_add_i32 s33, s42, 2
	s_add_u32 s46, s40, 0x80
	s_addc_u32 s43, s41, 0
	s_add_i32 s80, 0, 0x10000
	s_cmp_eq_u32 s84, s42
	s_cselect_b32 s43, s1, s43
	s_cselect_b32 s42, s0, s46
	s_cselect_b32 s47, s75, vcc_hi
	s_cselect_b32 s46, s74, vcc_lo
	s_add_i32 s5, 0, 0x14000
	ds_read_b128 v[128:131], v249
	ds_read_b128 v[132:135], v249 offset:1024
	ds_read_b128 v[136:139], v249 offset:2048
	ds_read_b128 v[140:143], v249 offset:3072
	ds_read_b128 v[144:147], v249 offset:16384
	ds_read_b128 v[148:151], v249 offset:17408
	ds_read_b128 v[152:155], v249 offset:18432
	ds_read_b128 v[166:169], v249 offset:19456
	v_lshl_add_u64 v[182:183], s[40:41], 0, v[162:163]
	s_add_i32 m0, s28, 0xc000
	ds_read_b128 v[170:173], v188
	ds_read_b128 v[174:177], v188 offset:1024
	ds_read_b128 v[178:181], v188 offset:2048
	ds_read_b128 v[214:217], v188 offset:3072
	ds_read_b128 v[218:221], v188 offset:4096
	ds_read_b128 v[222:225], v188 offset:5120
	ds_read_b128 v[226:229], v188 offset:6144
	ds_read_b128 v[230:233], v188 offset:7168
	global_load_lds_dwordx4 v[182:183], off
	v_lshl_add_u64 v[182:183], s[40:41], 0, v[164:165]
	s_add_i32 m0, s28, 0xe000
	s_nop 0
	global_load_lds_dwordx4 v[182:183], off
	s_waitcnt vmcnt(24)
	s_waitcnt lgkmcnt(0)
	s_barrier
	s_waitcnt lgkmcnt(0)
	v_mfma_f32_16x16x32_bf16 v[124:127], v[128:131], v[170:173], 0
	v_mfma_f32_16x16x32_bf16 v[120:123], v[136:139], v[170:173], 0
	v_mfma_f32_16x16x32_bf16 v[108:111], v[128:131], v[178:181], 0
	v_mfma_f32_16x16x32_bf16 v[104:107], v[136:139], v[178:181], 0
	v_mfma_f32_16x16x32_bf16 v[92:95], v[128:131], v[218:221], 0
	v_mfma_f32_16x16x32_bf16 v[88:91], v[136:139], v[218:221], 0
	v_mfma_f32_16x16x32_bf16 v[76:79], v[128:131], v[226:229], 0
	v_mfma_f32_16x16x32_bf16 v[72:75], v[136:139], v[226:229], 0
	v_mfma_f32_16x16x32_bf16 v[124:127], v[132:135], v[174:177], v[124:127]
	v_mfma_f32_16x16x32_bf16 v[120:123], v[140:143], v[174:177], v[120:123]
	v_mfma_f32_16x16x32_bf16 v[108:111], v[132:135], v[214:217], v[108:111]
	v_mfma_f32_16x16x32_bf16 v[104:107], v[140:143], v[214:217], v[104:107]
	v_mfma_f32_16x16x32_bf16 v[92:95], v[132:135], v[222:225], v[92:95]
	v_mfma_f32_16x16x32_bf16 v[88:91], v[140:143], v[222:225], v[88:91]
	v_mfma_f32_16x16x32_bf16 v[76:79], v[132:135], v[230:233], v[76:79]
	v_mfma_f32_16x16x32_bf16 v[72:75], v[140:143], v[230:233], v[72:75]
	v_mfma_f32_16x16x32_bf16 v[116:119], v[144:147], v[170:173], 0
	v_mfma_f32_16x16x32_bf16 v[112:115], v[152:155], v[170:173], 0
	v_mfma_f32_16x16x32_bf16 v[100:103], v[144:147], v[178:181], 0
	v_mfma_f32_16x16x32_bf16 v[96:99], v[152:155], v[178:181], 0
	v_mfma_f32_16x16x32_bf16 v[84:87], v[144:147], v[218:221], 0
	v_mfma_f32_16x16x32_bf16 v[80:83], v[152:155], v[218:221], 0
	v_mfma_f32_16x16x32_bf16 v[68:71], v[144:147], v[226:229], 0
	v_mfma_f32_16x16x32_bf16 v[64:67], v[152:155], v[226:229], 0
	v_mfma_f32_16x16x32_bf16 v[116:119], v[148:151], v[174:177], v[116:119]
	v_mfma_f32_16x16x32_bf16 v[112:115], v[166:169], v[174:177], v[112:115]
	v_mfma_f32_16x16x32_bf16 v[100:103], v[148:151], v[214:217], v[100:103]
	v_mfma_f32_16x16x32_bf16 v[96:99], v[166:169], v[214:217], v[96:99]
	v_mfma_f32_16x16x32_bf16 v[84:87], v[148:151], v[222:225], v[84:87]
	v_mfma_f32_16x16x32_bf16 v[80:83], v[166:169], v[222:225], v[80:83]
	v_mfma_f32_16x16x32_bf16 v[68:71], v[148:151], v[230:233], v[68:71]
	v_mfma_f32_16x16x32_bf16 v[64:67], v[166:169], v[230:233], v[64:67]
	s_barrier
	s_add_i32 s80, s80, s27
	s_mov_b32 m0, s80
	ds_read_b128 v[170:173], v188 offset:16384
	ds_read_b128 v[174:177], v188 offset:17408
	ds_read_b128 v[178:181], v188 offset:18432
	ds_read_b128 v[214:217], v188 offset:19456
	ds_read_b128 v[218:221], v188 offset:20480
	ds_read_b128 v[222:225], v188 offset:21504
	ds_read_b128 v[226:229], v188 offset:22528
	ds_read_b128 v[230:233], v188 offset:23552
	v_lshl_add_u64 v[182:183], s[46:47], 0, v[192:193]
	global_load_lds_dwordx4 v[182:183], off
	s_add_i32 m0, s80, 0x2000
	v_lshl_add_u64 v[190:191], s[46:47], 0, v[160:161]
	s_add_u32 s46, s46, s30
	s_addc_u32 s47, s47, 0
	s_add_i32 s5, s5, s27
	global_load_lds_dwordx4 v[190:191], off
	v_lshl_add_u64 v[200:201], s[46:47], 0, v[192:193]
	s_mov_b32 m0, s5
	v_lshl_add_u64 v[234:235], s[46:47], 0, v[160:161]
	global_load_lds_dwordx4 v[200:201], off
	s_add_i32 m0, s5, 0x2000
	v_lshl_add_u64 v[236:237], s[42:43], 0, v[156:157]
	global_load_lds_dwordx4 v[234:235], off
	s_mov_b32 m0, s28
	v_lshl_add_u64 v[238:239], s[42:43], 0, v[158:159]
	global_load_lds_dwordx4 v[236:237], off
	s_mov_b32 m0, s69
	s_nop 0
	global_load_lds_dwordx4 v[238:239], off
	s_waitcnt vmcnt(24)
	s_waitcnt lgkmcnt(0)
	s_barrier
	s_waitcnt lgkmcnt(0)
	v_mfma_f32_16x16x32_bf16 v[60:63], v[128:131], v[170:173], 0
	v_mfma_f32_16x16x32_bf16 v[56:59], v[136:139], v[170:173], 0
	v_mfma_f32_16x16x32_bf16 v[44:47], v[128:131], v[178:181], 0
	v_mfma_f32_16x16x32_bf16 v[40:43], v[136:139], v[178:181], 0
	v_mfma_f32_16x16x32_bf16 v[28:31], v[128:131], v[218:221], 0
	v_mfma_f32_16x16x32_bf16 v[24:27], v[136:139], v[218:221], 0
	v_mfma_f32_16x16x32_bf16 v[12:15], v[128:131], v[226:229], 0
	v_mfma_f32_16x16x32_bf16 v[8:11], v[136:139], v[226:229], 0
	v_mfma_f32_16x16x32_bf16 v[60:63], v[132:135], v[174:177], v[60:63]
	v_mfma_f32_16x16x32_bf16 v[56:59], v[140:143], v[174:177], v[56:59]
	v_mfma_f32_16x16x32_bf16 v[44:47], v[132:135], v[214:217], v[44:47]
	v_mfma_f32_16x16x32_bf16 v[40:43], v[140:143], v[214:217], v[40:43]
	v_mfma_f32_16x16x32_bf16 v[28:31], v[132:135], v[222:225], v[28:31]
	v_mfma_f32_16x16x32_bf16 v[24:27], v[140:143], v[222:225], v[24:27]
	v_mfma_f32_16x16x32_bf16 v[12:15], v[132:135], v[230:233], v[12:15]
	v_mfma_f32_16x16x32_bf16 v[8:11], v[140:143], v[230:233], v[8:11]
	v_mfma_f32_16x16x32_bf16 v[52:55], v[144:147], v[170:173], 0
	v_mfma_f32_16x16x32_bf16 v[48:51], v[152:155], v[170:173], 0
	v_mfma_f32_16x16x32_bf16 v[36:39], v[144:147], v[178:181], 0
	v_mfma_f32_16x16x32_bf16 v[32:35], v[152:155], v[178:181], 0
	v_mfma_f32_16x16x32_bf16 v[20:23], v[144:147], v[218:221], 0
	v_mfma_f32_16x16x32_bf16 v[16:19], v[152:155], v[218:221], 0
	v_mfma_f32_16x16x32_bf16 v[4:7], v[144:147], v[226:229], 0
	v_mfma_f32_16x16x32_bf16 v[0:3], v[152:155], v[226:229], 0
	v_mfma_f32_16x16x32_bf16 v[52:55], v[148:151], v[174:177], v[52:55]
	v_mfma_f32_16x16x32_bf16 v[48:51], v[166:169], v[174:177], v[48:51]
	v_mfma_f32_16x16x32_bf16 v[36:39], v[148:151], v[214:217], v[36:39]
	v_mfma_f32_16x16x32_bf16 v[32:35], v[166:169], v[214:217], v[32:35]
	v_mfma_f32_16x16x32_bf16 v[20:23], v[148:151], v[222:225], v[20:23]
	v_mfma_f32_16x16x32_bf16 v[16:19], v[166:169], v[222:225], v[16:19]
	v_mfma_f32_16x16x32_bf16 v[4:7], v[148:151], v[230:233], v[4:7]
	v_mfma_f32_16x16x32_bf16 v[0:3], v[166:169], v[230:233], v[0:3]
	s_barrier
	s_branch .Lmy_sp3
